# stagger + per-XCD job queues (refined ticket state machine) + head-coherent schedule table v2
# speedup vs baseline: 1.0122x; 1.0065x over previous
.LBB0_1575:
	s_and_saveexec_b64 s[4:5], s[6:7]
	s_cbranch_execz .LBB0_1579
	v_mov_b32_e32 v2, s57
	ds_read_b32 v0, v2 offset:4
	s_getreg_b32 s0, hwreg(HW_REG_XCC_ID, 0, 4)
	s_and_b32 s0, s0, 7
	s_waitcnt lgkmcnt(0)
	v_readfirstlane_b32 s8, v0
	s_cmp_lt_u32 s8, 16
	s_cbranch_scc1 .Lqa_loop
	s_and_b32 s8, s8, 15
	s_cmp_ge_u32 s8, 8
	s_cbranch_scc1 .Lqa_mem
	v_mov_b32_e32 v3, 32
	global_load_dword v3, v3, s[20:21] sc1
	s_waitcnt vmcnt(0)
	v_readfirstlane_b32 s9, v3
	s_cmpk_ge_u32 s9, 0x100
	s_cbranch_scc1 .Lqa_mem

.Lqa_got:
	v_mov_b32_e32 v0, 32
	v_mov_b32_e32 v2, 1
	global_atomic_add v0, v2, s[20:21]
	s_lshl_b32 s9, s9, 5
	s_add_i32 s15, s15, s9
	s_or_b32 s8, s8, 16
	s_branch .Lqa_pub
.Lqa_mem:
	s_mov_b32 s8, 24
	v_mov_b32_e32 v2, 1
	global_atomic_add v2, v1, v2, s[20:21] sc0
	s_waitcnt vmcnt(0)
	v_readfirstlane_b32 s15, v2
	s_addk_i32 s15, 0x100
	s_cmpk_lt_u32 s15, 0x200
	s_cbranch_scc1 .Lqa_pub
	s_movk_i32 s15, 0x200
	s_mov_b32 s8, 0

.LBB0_2128:
	s_and_saveexec_b64 s[4:5], s[6:7]
	s_cbranch_execz .LBB0_2132
	v_mov_b32_e32 v2, s64
	ds_read_b32 v0, v2 offset:4
	s_getreg_b32 s0, hwreg(HW_REG_XCC_ID, 0, 4)
	s_and_b32 s0, s0, 7
	s_waitcnt lgkmcnt(0)
	v_readfirstlane_b32 s8, v0
	s_cmp_lt_u32 s8, 16
	s_cbranch_scc1 .Lqb_loop
	s_and_b32 s8, s8, 15
	s_cmp_ge_u32 s8, 8
	s_cbranch_scc1 .Lqb_mem
	v_mov_b32_e32 v3, 32
	global_load_dword v3, v3, s[20:21] sc1
	s_waitcnt vmcnt(0)
	v_readfirstlane_b32 s9, v3
	s_cmpk_ge_u32 s9, 0x100
	s_cbranch_scc1 .Lqb_mem

_ZL10kAttnSched:
	.short	127
	.short	47
	.short	16
	.short	126
	.short	39
	.short	537
	.short	125
	.short	60
	.short	390
	.short	124
	.short	49
	.short	18
	.short	123
	.short	63
	.short	389
	.short	122
	.short	42
	.short	667
	.short	121
	.short	41
	.short	541
	.short	120
	.short	58
	.short	525
	.short	119
	.short	37
	.short	546
	.short	118
	.short	40
	.short	673
	.short	117
	.short	431
	.short	539
	.short	116
	.short	428
	.short	30
	.short	115
	.short	423
	.short	549
	.short	114
	.short	437
	.short	664
	.short	113
	.short	432
	.short	542
	.short	112
	.short	424
	.short	551
	.short	111
	.short	425
	.short	295
	.short	110
	.short	434
	.short	543
	.short	109
	.short	426
	.short	296
	.short	108
	.short	444
	.short	663
	.short	107
	.short	430
	.short	550
	.short	106
	.short	52
	.short	545
	.short	105
	.short	45
	.short	297
	.short	104
	.short	46
	.short	553
	.short	103
	.short	53
	.short	674
	.short	102
	.short	48
	.short	552
	.short	101
	.short	55
	.short	547
	.short	100
	.short	570
	.short	544
	.short	99
	.short	558
	.short	429
	.short	98
	.short	51
	.short	298
	.short	97
	.short	69
	.short	665
	.short	96
	.short	56
	.short	294
	.short	95
	.short	447
	.short	161
	.short	94
	.short	464
	.short	657
	.short	93
	.short	435
	.short	559
	.short	92
	.short	439
	.short	555
	.short	91
	.short	346
	.short	649
	.short	90
	.short	307
	.short	433
	.short	89
	.short	441
	.short	557
	.short	88
	.short	331
	.short	540
	.short	87
	.short	436
	.short	691
	.short	86
	.short	309
	.short	692
	.short	85
	.short	440
	.short	305
	.short	84
	.short	336
	.short	538
	.short	83
	.short	310
	.short	54
	.short	82
	.short	328
	.short	36
	.short	81
	.short	322
	.short	556
	.short	80
	.short	324
	.short	554
	.short	79
	.short	334
	.short	418
	.short	78
	.short	332
	.short	420
	.short	77
	.short	316
	.short	438
	.short	76
	.short	196
	.short	303
	.short	75
	.short	194
	.short	689
	.short	255
	.short	179
	.short	653
	.short	254
	.short	304
	.short	401
	.short	253
	.short	299
	.short	535
	.short	252
	.short	313
	.short	650
	.short	251
	.short	312
	.short	652
	.short	250
	.short	291
	.short	162
	.short	249
	.short	325
	.short	512
	.short	248
	.short	319
	.short	263
	.short	247
	.short	308
	.short	276
	.short	246
	.short	38
	.short	419
	.short	245
	.short	50
	.short	536
	.short	244
	.short	302
	.short	668
	.short	243
	.short	174
	.short	286
	.short	242
	.short	172
	.short	672
	.short	241
	.short	177
	.short	29
	.short	240
	.short	182
	.short	153
	.short	239
	.short	171
	.short	293
	.short	238
	.short	181
	.short	27
	.short	237
	.short	684
	.short	421
	.short	236
	.short	314
	.short	24
	.short	235
	.short	311
	.short	669
	.short	203
	.short	455
	.short	300
	.short	233
	.short	184
	.short	670
	.short	232
	.short	180
	.short	34
	.short	231
	.short	442
	.short	285
	.short	230
	.short	185
	.short	288
	.short	229
	.short	197
	.short	277
	.short	228
	.short	188
	.short	671
	.short	227
	.short	205
	.short	398
	.short	226
	.short	209
	.short	267
	.short	225
	.short	200
	.short	278
	.short	224
	.short	470
	.short	264
	.short	223
	.short	454
	.short	25
	.short	222
	.short	465
	.short	399
	.short	221
	.short	453
	.short	28
	.short	220
	.short	446
	.short	165
	.short	219
	.short	602
	.short	265
	.short	218
	.short	474
	.short	266
	.short	217
	.short	451
	.short	35
	.short	216
	.short	468
	.short	402
	.short	215
	.short	450
	.short	422
	.short	214
	.short	443
	.short	301
	.short	213
	.short	587
	.short	287
	.short	339
	.short	697
	.short	306
	.short	210
	.short	327
	.short	166
	.short	208
	.short	199
	.short	679
	.short	207
	.short	201
	.short	678
	.short	206
	.short	204
	.short	676
	.short	362
	.short	701
	.short	279
	.short	383
	.short	686
	.short	17
	.short	374
	.short	44
	.short	157
	.short	381
	.short	702
	.short	3
	.short	380
	.short	699
	.short	647
	.short	367
	.short	568
	.short	152
	.short	467
	.short	71
	.short	164
	.short	377
	.short	170
	.short	156
	.short	211
	.short	73
	.short	163
	.short	375
	.short	168
	.short	160
	.short	498
	.short	690
	.short	155
	.short	368
	.short	718
	.short	513
	.short	359
	.short	705
	.short	151
	.short	371
	.short	694
	.short	534
	.short	370
	.short	687
	.short	158
	.short	369
	.short	565
	.short	408
	.short	496
	.short	713
	.short	646
	.short	495
	.short	566
	.short	410
	.short	494
	.short	567
	.short	282
	.short	365
	.short	569
	.short	280
	.short	364
	.short	573
	.short	22
	.short	491
	.short	575
	.short	21
	.short	234
	.short	574
	.short	150
	.short	489
	.short	578
	.short	20
	.short	360
	.short	700
	.short	154
	.short	372
	.short	43
	.short	159
	.short	497
	.short	706
	.short	11
	.short	505
	.short	708
	.short	129
	.short	740
	.short	459
	.short	143
	.short	739
	.short	458
	.short	145
	.short	506
	.short	709
	.short	128
	.short	737
	.short	466
	.short	268
	.short	352
	.short	469
	.short	137
	.short	479
	.short	456
	.short	23
	.short	478
	.short	717
	.short	19
	.short	349
	.short	722
	.short	15
	.short	348
	.short	703
	.short	292
	.short	730
	.short	729
	.short	396
	.short	345
	.short	726
	.short	271
	.short	728
	.short	727
	.short	655
	.short	471
	.short	711
	.short	417
	.short	342
	.short	72
	.short	32
	.short	378
	.short	696
	.short	13
	.short	719
	.short	457
	.short	167
	.short	462
	.short	461
	.short	548
	.short	355
	.short	340
	.short	391
	.short	767
	.short	427
	.short	149
	.short	358
	.short	452
	.short	148
	.short	376
	.short	677
	.short	289
	.short	508
	.short	675
	.short	31
	.short	351
	.short	460
	.short	147
	.short	502
	.short	680
	.short	33
	.short	761
	.short	698
	.short	12
	.short	504
	.short	695
	.short	656
	.short	503
	.short	693
	.short	146
	.short	766
	.short	688
	.short	144
	.short	373
	.short	682
	.short	416
	.short	500
	.short	685
	.short	414
	.short	501
	.short	683
	.short	415
	.short	482
	.short	712
	.short	532
	.short	382
	.short	449
	.short	256
	.short	624
	.short	333
	.short	642
	.short	379
	.short	315
	.short	648
	.short	366
	.short	318
	.short	658
	.short	493
	.short	317
	.short	533
	.short	492
	.short	320
	.short	275
	.short	363
	.short	66
	.short	274
	.short	618
	.short	704
	.short	661
	.short	617
	.short	74
	.short	651
	.short	488
	.short	61
	.short	26
	.short	635
	.short	321
	.short	130
	.short	486
	.short	710
	.short	530
	.short	613
	.short	725
	.short	4
	.short	484
	.short	716
	.short	142
	.short	611
	.short	720
	.short	139
	.short	354
	.short	724
	.short	136
	.short	609
	.short	714
	.short	531
	.short	480
	.short	600
	.short	134
	.short	487
	.short	707
	.short	660
	.short	350
	.short	603
	.short	6
	.short	477
	.short	343
	.short	138
	.short	476
	.short	347
	.short	135
	.short	598
	.short	338
	.short	662
	.short	481
	.short	593
	.short	140
	.short	639
	.short	445
	.short	643
	.short	511
	.short	448
	.short	640
	.short	509
	.short	564
	.short	141
	.short	361
	.short	721
	.short	644
	.short	507
	.short	577
	.short	131
	.short	634
	.short	579
	.short	258
	.short	633
	.short	562
	.short	659
	.short	632
	.short	186
	.short	397
	.short	631
	.short	190
	.short	10
	.short	630
	.short	176
	.short	409
	.short	629
	.short	173
	.short	413
	.short	628
	.short	169
	.short	290
	.short	499
	.short	561
	.short	411
	.short	626
	.short	178
	.short	283
	.short	625
	.short	191
	.short	270
	.short	627
	.short	175
	.short	412
	.short	623
	.short	183
	.short	281
	.short	622
	.short	189
	.short	403
	.short	621
	.short	187
	.short	407
	.short	620
	.short	195
	.short	272
	.short	619
	.short	202
	.short	394
	.short	490
	.short	192
	.short	404
	.short	636
	.short	57
	.short	9
	.short	616
	.short	326
	.short	273
	.short	615
	.short	329
	.short	654
	.short	614
	.short	323
	.short	406
	.short	485
	.short	344
	.short	257
	.short	612
	.short	337
	.short	393
	.short	483
	.short	341
	.short	262
	.short	610
	.short	335
	.short	269
	.short	637
	.short	65
	.short	641
	.short	608
	.short	473
	.short	645
	.short	607
	.short	475
	.short	260
	.short	606
	.short	472
	.short	392
	.short	605
	.short	601
	.short	8
	.short	604
	.short	599
	.short	395
	.short	595
	.short	463
	.short	284
	.short	638
	.short	59
	.short	261
	.short	510
	.short	62
	.short	259
	.short	765
	.short	563
	.short	526
	.short	764
	.short	572
	.short	7
	.short	763
	.short	64
	.short	388
	.short	762
	.short	68
	.short	1
	.short	741
	.short	592
	.short	521
	.short	760
	.short	67
	.short	515
	.short	759
	.short	70
	.short	2
	.short	758
	.short	198
	.short	387
	.short	757
	.short	560
	.short	666
	.short	756
	.short	571
	.short	527
	.short	755
	.short	583
	.short	133
	.short	754
	.short	586
	.short	514
	.short	753
	.short	582
	.short	519
	.short	752
	.short	591
	.short	0
	.short	751
	.short	580
	.short	524
	.short	750
	.short	581
	.short	523
	.short	749
	.short	193
	.short	529
	.short	748
	.short	589
	.short	517
	.short	747
	.short	590
	.short	5
	.short	746
	.short	576
	.short	405
	.short	745
	.short	212
	.short	385
	.short	744
	.short	596
	.short	386
	.short	743
	.short	585
	.short	14
	.short	742
	.short	584
	.short	400
	.short	357
	.short	597
	.short	516
	.short	356
	.short	594
	.short	520
	.short	715
	.short	330
	.short	681
	.short	738
	.short	588
	.short	528
	.short	353
	.short	723
	.short	522
	.short	736
	.short	735
	.short	384
	.short	734
	.short	732
	.short	132
	.short	733
	.short	731
	.short	518
	.size	_ZL10kAttnSched, 1536

	.type	__hip_cuid_2978c3a30ac043b7,@object
